# rwkv light prep: both items' LDS reads issued at the chunk-loop top, on top of the lean prefetch fast path
# baseline (speedup 1.0000x reference)
; template <bool DUAL>
; __device__ __forceinline__ void rwkv_tile(const Params& p, int l, int tile, unsigned char* smem) {
;     ...
;       const int i = (tid >> 4) + 16 * k;
;       const int ri = (d == 0) ? i + 1 : 32 - i;
;       const bf16_t* r0 = raw + ri * 192 + lc;
;       const bf16_t* q0 = pre + (ri - 1) * 192 + lc;
;       float rs[4], ksv[4], vs[4];
; #pragma unroll
;       for (int sl = 0; sl < 3; ++sl) {
;         const uint2 uc = *(const uint2*)(r0 + sl * 64), up = *(const uint2*)(r0 + sl * 64 - 192), un = *(const uint2*)(r0 + sl * 64 + 192);
;         const float4 m0 = (sl == 0) ? m0r : ((sl == 1) ? m0k : m0v);
;         const float4 m1 = (sl == 0) ? m1r : ((sl == 1) ? m1k : m1v);
;         float* dst = (sl == 0) ? rs : ((sl == 1) ? ksv : vs);
;         float u, a, n;
;         u = __uint_as_float(uc.x << 16); a = __uint_as_float(up.x << 16); n = __uint_as_float(un.x << 16);
;         dst[0] = u + m0.x * (a - u) + m1.x * (n - u);
;         u = __uint_as_float(uc.x & 0xffff0000u); a = __uint_as_float(up.x & 0xffff0000u); n = __uint_as_float(un.x & 0xffff0000u);
;         dst[1] = u + m0.y * (a - u) + m1.y * (n - u);
;         u = __uint_as_float(uc.y << 16); a = __uint_as_float(up.y << 16); n = __uint_as_float(un.y << 16);
;         dst[2] = u + m0.z * (a - u) + m1.z * (n - u);
;         u = __uint_as_float(uc.y & 0xffff0000u); a = __uint_as_float(up.y & 0xffff0000u); n = __uint_as_float(un.y & 0xffff0000u);
;         dst[3] = u + m0.w * (a - u) + m1.w * (n - u);
;       }
;       const uint2 ue = *(const uint2*)(q0), ua = *(const uint2*)(q0 + 64), uk = *(const uint2*)(q0 + 128);
.LBB0_1411:
	ds_read2_b64 v[60:63], v107 offset1:16
	ds_read_b64 v[72:73], v108
	ds_read2_b64 v[64:67], v107 offset0:32 offset1:48
	ds_read_b64 v[76:77], v109
	ds_read_b64 v[78:79], v110
	ds_read_b64 v[122:123], v111 offset:12928
	ds_read2_b64 v[68:71], v107 offset0:64 offset1:80
	ds_read2_b64 v[216:219], v112 offset1:16
	ds_read_b64 v[156:157], v113
	ds_read2_b64 v[220:223], v112 offset0:32 offset1:48
	ds_read_b64 v[160:161], v114
	ds_read_b64 v[162:163], v115
	ds_read_b64 v[228:229], v116 offset:12928
	ds_read2_b64 v[224:227], v112 offset0:64 offset1:80
	s_add_i32 s52, s28, 1
	s_cmpk_eq_i32 s28, 0x87
	s_cbranch_scc1 .Lrw_du_nopf
	s_lshl_b32 s53, s52, 5
	s_sub_i32 s54, 0x11e0, s53
	s_and_b64 s[50:51], s[36:37], exec
	s_cselect_b32 s53, s53, s54
	s_add_i32 s54, s53, -1
	s_cmpk_eq_u32 s52, 0x87
	s_cbranch_scc1 .Lrw_du_pfslow
	s_and_saveexec_b64 s[50:51], s[42:43]
	s_ashr_i32 s101, s54, 31
	s_mov_b32 s100, s54
	s_lshl_b64 s[100:101], s[100:101], 11
	v_lshl_add_u64 v[40:41], v[80:81], 0, s[100:101]
	s_ashr_i32 s101, s53, 31
	s_mov_b32 s100, s53
	s_lshl_b64 s[100:101], s[100:101], 10
	v_lshl_add_u64 v[56:57], v[82:83], 0, s[100:101]
	v_lshl_add_u64 v[32:33], v[242:243], 1, v[40:41]
	global_load_dwordx4 v[32:35], v[32:33], off
	v_lshl_add_u64 v[28:29], v[244:245], 1, v[40:41]
	global_load_dwordx4 v[28:31], v[28:29], off
	v_lshl_add_u64 v[36:37], v[246:247], 1, v[40:41]
	global_load_dwordx4 v[36:39], v[36:37], off
	v_lshl_add_u64 v[44:45], v[242:243], 0, v[56:57]
	global_load_dwordx4 v[44:47], v[44:45], off
	v_lshl_add_u64 v[48:49], v[244:245], 0, v[56:57]
	global_load_dwordx4 v[48:51], v[48:49], off
	v_lshl_add_u64 v[52:53], v[246:247], 0, v[56:57]
	global_load_dwordx4 v[52:55], v[52:53], off
	s_mov_b64 exec, s[50:51]
	s_and_b64 exec, exec, s[44:45]
	v_lshl_add_u64 v[40:41], v[248:249], 1, v[40:41]
	global_load_dwordx4 v[40:43], v[40:41], off
	s_mov_b64 exec, s[50:51]
	s_and_b64 exec, exec, s[46:47]
	v_lshl_add_u64 v[56:57], v[248:249], 0, v[56:57]
	global_load_dwordx4 v[56:59], v[56:57], off
	s_mov_b64 exec, s[50:51]
	s_branch .Lrw_du_nopf

; template <bool DUAL>
; __device__ __forceinline__ void rwkv_tile(const Params& p, int l, int tile, unsigned char* smem) {
;     ...
;   for (int cix = cbeg; cix < cend; ++cix) {
;     int plo, slo, shi;
;     RW_GEOM(cix, plo, slo, shi);
; #pragma unroll
;     for (int k = 0; k < 2; ++k) {
;       const int i = (tid >> 4) + 16 * k;
;       const int ri = (d == 0) ? i + 1 : 32 - i;
;       const bf16_t* r0 = raw + ri * 192 + lc;
;       const bf16_t* q0 = pre + (ri - 1) * 192 + lc;
;       float rs[4], ksv[4], vs[4];
; #pragma unroll
;       for (int sl = 0; sl < 3; ++sl) {
;         const uint2 uc = *(const uint2*)(r0 + sl * 64), up = *(const uint2*)(r0 + sl * 64 - 192), un = *(const uint2*)(r0 + sl * 64 + 192);
.LBB0_1468:
	ds_read2_b64 v[64:67], v104 offset1:16
	ds_read_b64 v[76:77], v105
	ds_read2_b64 v[68:71], v104 offset0:32 offset1:48
	ds_read_b64 v[80:81], v106
	ds_read_b64 v[82:83], v107
	ds_read_b64 v[118:119], v108 offset:12928
	ds_read2_b64 v[72:75], v104 offset0:64 offset1:80
	ds_read2_b64 v[216:219], v109 offset1:16
	ds_read_b64 v[152:153], v110
	ds_read2_b64 v[220:223], v109 offset0:32 offset1:48
	ds_read_b64 v[156:157], v111
	ds_read_b64 v[158:159], v112
	ds_read_b64 v[160:161], v113 offset:12928
	ds_read2_b64 v[224:227], v109 offset0:64 offset1:80
	s_add_i32 s56, s28, 1
	v_readlane_b32 s0, v254, 14
	s_cmp_ge_u32 s56, s0
	s_cbranch_scc1 .Lrw_nd_nopf
	s_lshl_b32 s57, s56, 5
	s_sub_i32 s58, 0xe0, s57
	s_and_b64 s[50:51], s[36:37], exec
	s_cselect_b32 s64, s57, s58
	s_sub_i32 s58, 0x11e0, s57
	s_and_b64 s[50:51], s[36:37], exec
	s_cselect_b32 s50, s57, s58
	s_cmp_lt_u32 s28, 7
	s_movk_i32 s0, 0x10ff
	s_cselect_b32 s57, s64, s50
	s_cselect_b32 s58, 0xff, s0
	s_cselect_b32 s59, 0, 0x100
	s_add_i32 s66, s57, -1
	s_cmp_eq_u32 s56, 7
	s_cbranch_scc1 .Lrw_nd_pfslow
	s_cmp_eq_u32 s56, 8
	s_cbranch_scc1 .Lrw_nd_pfslow
	s_cmpk_eq_u32 s56, 0x87
	s_cbranch_scc1 .Lrw_nd_pfslow
	s_and_saveexec_b64 s[50:51], s[42:43]
	s_ashr_i32 s101, s66, 31
	s_mov_b32 s100, s66
	s_lshl_b64 s[100:101], s[100:101], 11
	v_lshl_add_u64 v[40:41], v[84:85], 0, s[100:101]
	s_ashr_i32 s101, s57, 31
	s_mov_b32 s100, s57
	s_lshl_b64 s[100:101], s[100:101], 10
	v_lshl_add_u64 v[56:57], v[86:87], 0, s[100:101]
	v_lshl_add_u64 v[32:33], v[242:243], 1, v[40:41]
	global_load_dwordx4 v[32:35], v[32:33], off
	v_lshl_add_u64 v[28:29], v[244:245], 1, v[40:41]
	global_load_dwordx4 v[28:31], v[28:29], off
	v_lshl_add_u64 v[36:37], v[246:247], 1, v[40:41]
	global_load_dwordx4 v[36:39], v[36:37], off
	v_lshl_add_u64 v[44:45], v[242:243], 0, v[56:57]
	global_load_dwordx4 v[44:47], v[44:45], off
	v_lshl_add_u64 v[48:49], v[244:245], 0, v[56:57]
	global_load_dwordx4 v[48:51], v[48:49], off
	v_lshl_add_u64 v[52:53], v[246:247], 0, v[56:57]
	global_load_dwordx4 v[52:55], v[52:53], off
	s_mov_b64 exec, s[50:51]
	s_andn2_b64 exec, exec, s[46:47]
	v_lshl_add_u64 v[40:41], v[248:249], 1, v[40:41]
	global_load_dwordx4 v[40:43], v[40:41], off
	s_mov_b64 exec, s[50:51]
	s_and_b64 exec, exec, s[48:49]
	v_lshl_add_u64 v[56:57], v[248:249], 0, v[56:57]
	global_load_dwordx4 v[56:59], v[56:57], off
	s_mov_b64 exec, s[50:51]
	s_branch .Lrw_nd_nopf
